# removed the redundant end-of-NSA-item workgroup barrier (the queue loop top barrier follows with no LDS access in between)
# baseline (speedup 1.0000x reference)
; DI unsigned pk2(float a, float b) { const f32x2_t f = {a, b}; const bf16x2_t r = __builtin_convertvector(f, bf16x2_t); return __builtin_bit_cast(unsigned, r); }
; DI void gla_item(const float* wgate, const float* bgate, const bf16_t* proj, bf16_t* mix, int item, LP unsigned char* lds3) {
;     ...
;   const int d = tid & 127, tq = tid >> 7;
;   float wg[16];
; #pragma unroll
;   for (int q = 0; q < 16; ++q) wg[q] = wgate[q * 512 + h * 128 + d];
;   const float bgv = bgate[h * 128 + d];
;   for (int i = tid; i < 128 * 136 / 2; i += 512) ((unsigned*)ST)[i] = 0u;
; DI void nsa_item(unsigned char* ws_, const float* qg, const bf16_t* proj, bf16_t* mix, int item, LP unsigned char* lds3) {
;     ...
;   { const float sc = g2 / lsum;
; #pragma unroll
;     for (int i = 0; i < 16; ++i) { o[0][i] = cmb[i * 512] + o[0][i] * sc; o[1][i] = cmb[(16 + i) * 512] + o[1][i] * sc; } }
;   bf16_t* op = mix + (size_t)(b * 2048 + t) * 2048 + 1024 + (g * 4 + hd) * 64;
; #pragma unroll
;   for (int dt = 0; dt < 2; ++dt)
; #pragma unroll
;     for (int gq = 0; gq < 4; ++gq) { u32x2 w; w.x = pk2(o[dt][4 * gq], o[dt][4 * gq + 1]); w.y = pk2(o[dt][4 * gq + 2], o[dt][4 * gq + 3]);
;       *(u32x2*)(op + dt * 32 + 8 * gq + 4 * hh) = w; }
;   __syncthreads();
.LBB0_644:
	s_or_b64 exec, exec, s[2:3]
	v_lshlrev_b32_e32 v38, 16, v99
	v_mul_f32_e32 v38, 0xbfb8aa3b, v38
	v_exp_f32_e32 v38, v38
	v_lshlrev_b32_e32 v168, 7, v98
	v_add_f32_e32 v38, 1.0, v38
	v_div_scale_f32 v44, s[2:3], v38, v38, 1.0
	v_rcp_f32_e32 v45, v44
	s_nop 0
	v_fma_f32 v46, -v44, v45, 1.0
	v_fmac_f32_e32 v45, v46, v45
	v_div_scale_f32 v46, vcc, 1.0, v38, 1.0
	v_mul_f32_e32 v47, v46, v45
	v_fma_f32 v52, -v44, v47, v46
	v_fmac_f32_e32 v47, v52, v45
	v_fma_f32 v44, -v44, v47, v46
	v_div_fmas_f32 v44, v44, v45, v47
	v_div_fixup_f32 v38, v44, v38, 1.0
	v_div_scale_f32 v44, s[2:3], v36, v36, v38
	v_rcp_f32_e32 v45, v44
	v_readlane_b32 s2, v252, 42
	v_readlane_b32 s3, v252, 43
	v_fma_f32 v46, -v44, v45, 1.0
	v_fmac_f32_e32 v45, v46, v45
	v_div_scale_f32 v46, vcc, v38, v36, v38
	v_mul_f32_e32 v47, v46, v45
	v_fma_f32 v52, -v44, v47, v46
	v_fmac_f32_e32 v47, v52, v45
	v_fma_f32 v44, -v44, v47, v46
	v_div_fmas_f32 v44, v44, v45, v47
	ds_read2st64_b32 v[46:47], v105 offset1:8
	ds_read2st64_b32 v[52:53], v105 offset0:120 offset1:128
	v_div_fixup_f32 v44, v44, v36, v38
	v_pk_fma_f32 v[12:13], v[44:45], v[12:13], v[50:51] op_sel_hi:[0,1,1]
	v_mov_b32_e32 v38, v43
	s_waitcnt lgkmcnt(1)
	v_pk_fma_f32 v[0:1], v[44:45], v[0:1], v[46:47] op_sel_hi:[0,1,1]
	ds_read2st64_b32 v[46:47], v105 offset0:136 offset1:144
	s_waitcnt lgkmcnt(1)
	v_mov_b32_e32 v54, v53
	v_cvt_pk_bf16_f32 v0, v0, v1
	v_pk_fma_f32 v[26:27], v[44:45], v[26:27], v[38:39] op_sel_hi:[0,1,1]
	v_pk_fma_f32 v[28:29], v[44:45], v[28:29], v[48:49] op_sel_hi:[0,1,1]
	s_waitcnt lgkmcnt(0)
	v_mov_b32_e32 v55, v46
	v_pk_fma_f32 v[16:17], v[44:45], v[16:17], v[54:55] op_sel_hi:[0,1,1]
	ds_read2st64_b32 v[54:55], v105 offset0:16 offset1:24
	v_mov_b32_e32 v46, v47
	s_waitcnt lgkmcnt(0)
	v_pk_fma_f32 v[2:3], v[44:45], v[2:3], v[54:55] op_sel_hi:[0,1,1]
	ds_read2st64_b32 v[54:55], v105 offset0:152 offset1:160
	v_cvt_pk_bf16_f32 v1, v2, v3
	s_waitcnt lgkmcnt(0)
	v_mov_b32_e32 v47, v54
	v_pk_fma_f32 v[18:19], v[44:45], v[18:19], v[46:47] op_sel_hi:[0,1,1]
	ds_read2st64_b32 v[46:47], v105 offset0:32 offset1:40
	v_mov_b32_e32 v54, v55
	s_waitcnt lgkmcnt(0)
	v_pk_fma_f32 v[4:5], v[44:45], v[4:5], v[46:47] op_sel_hi:[0,1,1]
	ds_read2st64_b32 v[46:47], v105 offset0:168 offset1:176
	s_waitcnt lgkmcnt(0)
	v_mov_b32_e32 v55, v46
	v_pk_fma_f32 v[20:21], v[44:45], v[20:21], v[54:55] op_sel_hi:[0,1,1]
	ds_read2st64_b32 v[54:55], v105 offset0:48 offset1:112
	s_waitcnt lgkmcnt(0)
	v_mov_b32_e32 v36, v54
	v_pk_fma_f32 v[6:7], v[44:45], v[6:7], v[36:37] op_sel_hi:[0,1,1]
	v_mov_b32_e32 v37, v33
	v_mov_b32_e32 v33, v34
	v_pk_fma_f32 v[8:9], v[44:45], v[8:9], v[32:33] op_sel_hi:[0,1,1]
	v_mov_b32_e32 v32, v35
	v_mov_b32_e32 v33, v41
	v_pk_fma_f32 v[24:25], v[44:45], v[24:25], v[32:33] op_sel_hi:[0,1,1]
	ds_read2st64_b32 v[32:33], v105 offset0:240 offset1:248
	v_mov_b32_e32 v41, v42
	v_pk_fma_f32 v[10:11], v[44:45], v[10:11], v[40:41] op_sel_hi:[0,1,1]
	v_mov_b32_e32 v34, v55
	v_mov_b32_e32 v35, v52
	s_waitcnt lgkmcnt(0)
	v_pk_fma_f32 v[30:31], v[44:45], v[30:31], v[32:33] op_sel_hi:[0,1,1]
	v_lshlrev_b64 v[32:33], 12, v[88:89]
	v_lshl_add_u64 v[32:33], s[2:3], 0, v[32:33]
	v_lshl_add_u64 v[32:33], v[32:33], 0, v[168:169]
	v_lshlrev_b32_e32 v168, 1, v104
	v_lshl_add_u64 v[32:33], v[32:33], 0, v[168:169]
	global_store_dwordx2 v[32:33], v[0:1], off offset:2048
	v_cvt_pk_bf16_f32 v0, v4, v5
	v_cvt_pk_bf16_f32 v1, v6, v7
	v_pk_fma_f32 v[14:15], v[44:45], v[14:15], v[34:35] op_sel_hi:[0,1,1]
	global_store_dwordx2 v[32:33], v[0:1], off offset:2064
	v_cvt_pk_bf16_f32 v0, v8, v9
	v_cvt_pk_bf16_f32 v1, v10, v11
	v_mov_b32_e32 v36, v47
	global_store_dwordx2 v[32:33], v[0:1], off offset:2080
	v_cvt_pk_bf16_f32 v0, v12, v13
	v_cvt_pk_bf16_f32 v1, v14, v15
	v_pk_fma_f32 v[22:23], v[44:45], v[22:23], v[36:37] op_sel_hi:[0,1,1]
	global_store_dwordx2 v[32:33], v[0:1], off offset:2096
	v_cvt_pk_bf16_f32 v0, v16, v17
	v_cvt_pk_bf16_f32 v1, v18, v19
	global_store_dwordx2 v[32:33], v[0:1], off offset:2112
	v_cvt_pk_bf16_f32 v0, v20, v21
	v_cvt_pk_bf16_f32 v1, v22, v23
	global_store_dwordx2 v[32:33], v[0:1], off offset:2128
	v_cvt_pk_bf16_f32 v0, v24, v25
	v_cvt_pk_bf16_f32 v1, v26, v27
	global_store_dwordx2 v[32:33], v[0:1], off offset:2144
	v_cvt_pk_bf16_f32 v0, v28, v29
	v_cvt_pk_bf16_f32 v1, v30, v31
	global_store_dwordx2 v[32:33], v[0:1], off offset:2160
.LBB0_645:
	v_readlane_b32 s2, v252, 54
	v_readlane_b32 s3, v252, 55
	s_andn2_saveexec_b64 s[54:55], s[2:3]
	s_cbranch_execz .LBB0_389
	v_readlane_b32 s2, v252, 38
	v_readlane_b32 s3, v252, 39
	s_load_dwordx4 s[8:11], s[2:3], 0x60
	v_mov_b32_e32 v1, v185
	v_bfe_u32 v4, v3, 1, 2
	v_lshlrev_b32_e32 v8, 7, v4
	v_and_b32_e32 v0, 0x7f, v1
	v_or_b32_e32 v2, v0, v8
	v_lshlrev_b32_e32 v168, 2, v2
	s_waitcnt lgkmcnt(0)
	v_lshl_add_u64 v[6:7], s[8:9], 0, v[168:169]
	v_add_co_u32_e32 v10, vcc, 0x1000, v6
	global_load_dword v57, v168, s[8:9] offset:2048
	s_nop 0
	v_addc_co_u32_e32 v11, vcc, 0, v7, vcc
	v_add_co_u32_e32 v12, vcc, 0x2000, v6
	s_movk_i32 s2, 0x2200
	s_nop 0
	v_addc_co_u32_e32 v13, vcc, 0, v7, vcc
	v_add_co_u32_e32 v14, vcc, 0x3000, v6
	s_nop 1
	v_addc_co_u32_e32 v15, vcc, 0, v7, vcc
	v_add_co_u32_e32 v16, vcc, 0x4000, v6
	s_nop 1
	v_addc_co_u32_e32 v17, vcc, 0, v7, vcc
	global_load_dword v67, v[10:11], off
	global_load_dword v71, v[10:11], off offset:2048
	global_load_dword v73, v[12:13], off
	global_load_dword v75, v[12:13], off offset:2048
	global_load_dword v77, v[14:15], off
	global_load_dword v79, v[14:15], off offset:2048
	global_load_dword v81, v[16:17], off
	global_load_dword v83, v[16:17], off offset:2048
	v_add_co_u32_e32 v10, vcc, 0x5000, v6
	s_nop 1
	v_addc_co_u32_e32 v11, vcc, 0, v7, vcc
	v_add_co_u32_e32 v12, vcc, 0x6000, v6
	s_nop 1
	v_addc_co_u32_e32 v13, vcc, 0, v7, vcc
	v_add_co_u32_e32 v6, vcc, 0x7000, v6
	s_nop 1
	v_addc_co_u32_e32 v7, vcc, 0, v7, vcc
	global_load_dword v85, v168, s[8:9]
	global_load_dword v87, v[10:11], off
	global_load_dword v89, v[10:11], off offset:2048
	global_load_dword v91, v[12:13], off
	global_load_dword v93, v[12:13], off offset:2048
	global_load_dword v95, v[6:7], off
	global_load_dword v97, v168, s[10:11]
	global_load_dword v99, v[6:7], off offset:2048
	v_cmp_gt_i32_e32 vcc, s2, v1
	s_and_saveexec_b64 s[2:3], vcc
	s_cbranch_execz .LBB0_649
	v_readlane_b32 s4, v252, 21
	v_add_u32_e32 v2, 0xfffffe00, v1
	s_nop 0
	v_lshl_add_u32 v5, v1, 2, s4
	s_mov_b64 s[4:5], 0
